# rmsnorm scale cache fill: both row loads issued together (was load-wait-compute twice), on top of de-serialised GEMM prologues + epilogue address trim
# baseline (speedup 1.0000x reference)
.LBB0_150:
	s_lshl_b32 s2, s30, 8
	s_cmp_eq_u32 s30, s70
	s_movk_i32 s74, 0x2000
	s_cbranch_scc1 .LBB0_152
	s_add_i32 s5, s2, s57
	v_mbcnt_lo_u32_b32 v136, -1, 0
	v_mbcnt_hi_u32_b32 v136, -1, v136
	s_mov_b32 s70, s30
	v_add_u32_e32 v132, s5, v136
	v_ashrrev_i32_e32 v133, 31, v132
	v_lshl_add_u64 v[134:135], v[132:133], 3, s[16:17]
	global_load_dwordx2 v[226:227], v[134:135], off offset:1024
	global_load_dwordx2 v[134:135], v[134:135], off
	v_add_u32_e32 v132, 0x80, v132
	s_waitcnt vmcnt(0)
	v_ffbh_u32_e32 v133, v135
	v_min_u32_e32 v133, 32, v133
	v_lshlrev_b64 v[134:135], v133, v[134:135]
	v_min_u32_e32 v134, 1, v134
	v_or_b32_e32 v134, v135, v134
	v_cvt_f32_u32_e32 v134, v134
	v_sub_u32_e32 v133, 32, v133
	v_ldexp_f32 v133, v134, v133
	v_mul_f32_e32 v133, 0x33800000, v133
	v_fmamk_f32 v133, v133, 0x3a000000, v224
	v_cmp_gt_f32_e32 vcc, s89, v133
	v_mul_f32_e32 v134, 0x4f800000, v133
	s_nop 0
	v_cndmask_b32_e32 v133, v133, v134, vcc
	v_sqrt_f32_e32 v134, v133
	s_nop 0
	v_add_u32_e32 v135, -1, v134
	v_fma_f32 v137, -v135, v134, v133
	v_cmp_ge_f32_e64 s[40:41], 0, v137
	v_add_u32_e32 v137, 1, v134
	s_nop 0
	v_cndmask_b32_e64 v135, v134, v135, s[40:41]
	v_fma_f32 v134, -v137, v134, v133
	v_cmp_lt_f32_e64 s[40:41], 0, v134
	s_nop 1
	v_cndmask_b32_e64 v134, v135, v137, s[40:41]
	v_mul_f32_e32 v135, 0x37800000, v134
	v_cndmask_b32_e32 v134, v134, v135, vcc
	v_cmp_class_f32_e32 vcc, v133, v225
	s_nop 1
	v_cndmask_b32_e32 v133, v134, v133, vcc
	v_div_scale_f32 v134, s[40:41], v133, v133, 1.0
	v_rcp_f32_e32 v135, v134
	s_nop 0
	v_fma_f32 v137, -v134, v135, 1.0
	v_fmac_f32_e32 v135, v137, v135
	v_div_scale_f32 v137, vcc, 1.0, v133, 1.0
	v_mul_f32_e32 v138, v137, v135
	v_fma_f32 v139, -v134, v138, v137
	v_fmac_f32_e32 v138, v139, v135
	v_fma_f32 v134, -v134, v138, v137
	v_div_fmas_f32 v134, v134, v135, v138
	v_div_fixup_f32 v134, v134, v133, 1.0
	v_mov_b32_e32 v132, v226
	v_mov_b32_e32 v133, v227
	v_lshl_add_u32 v135, v136, 2, s58
	s_waitcnt vmcnt(0)
	v_ffbh_u32_e32 v136, v133
	v_min_u32_e32 v136, 32, v136
	v_lshlrev_b64 v[132:133], v136, v[132:133]
	v_min_u32_e32 v132, 1, v132
	v_or_b32_e32 v132, v133, v132
	v_cvt_f32_u32_e32 v132, v132
	v_sub_u32_e32 v133, 32, v136
	v_ldexp_f32 v132, v132, v133
	v_mul_f32_e32 v132, 0x33800000, v132
	v_fmamk_f32 v132, v132, 0x3a000000, v224
	v_cmp_gt_f32_e32 vcc, s89, v132
	v_mul_f32_e32 v133, 0x4f800000, v132
	s_nop 0
	v_cndmask_b32_e32 v132, v132, v133, vcc
	v_sqrt_f32_e32 v133, v132
	s_nop 0
	v_add_u32_e32 v136, -1, v133
	v_fma_f32 v137, -v136, v133, v132
	v_cmp_ge_f32_e64 s[40:41], 0, v137
	v_add_u32_e32 v137, 1, v133
	s_nop 0
	v_cndmask_b32_e64 v136, v133, v136, s[40:41]
	v_fma_f32 v133, -v137, v133, v132
	v_cmp_lt_f32_e64 s[40:41], 0, v133
	s_nop 1
	v_cndmask_b32_e64 v133, v136, v137, s[40:41]
	v_mul_f32_e32 v136, 0x37800000, v133
	v_cndmask_b32_e32 v133, v133, v136, vcc
	v_cmp_class_f32_e32 vcc, v132, v225
	s_nop 1
	v_cndmask_b32_e32 v132, v133, v132, vcc
	v_div_scale_f32 v133, s[40:41], v132, v132, 1.0
	v_rcp_f32_e32 v136, v133
	s_nop 0
	v_fma_f32 v137, -v133, v136, 1.0
	v_fmac_f32_e32 v136, v137, v136
	v_div_scale_f32 v137, vcc, 1.0, v132, 1.0
	v_mul_f32_e32 v138, v137, v136
	v_fma_f32 v139, -v133, v138, v137
	v_fmac_f32_e32 v138, v139, v136
	v_fma_f32 v133, -v133, v138, v137
	v_div_fmas_f32 v133, v133, v136, v138
	v_div_fixup_f32 v132, v133, v132, 1.0
	ds_write2st64_b32 v135, v134, v132 offset1:1
	s_waitcnt lgkmcnt(0)

.LBB0_214:
	s_lshl_b32 s19, s26, 8
	v_readlane_b32 s56, v253, 10
	s_cmp_eq_u32 s26, s51
	s_movk_i32 s53, 0x4000
	s_movk_i32 s54, 0x5000
	v_readlane_b32 s57, v253, 11
	s_cbranch_scc1 .LBB0_216
	s_add_i32 s21, s19, s46
	v_mbcnt_lo_u32_b32 v144, -1, 0
	v_mbcnt_hi_u32_b32 v144, -1, v144
	s_mov_b32 s51, s26
	v_add_u32_e32 v140, s21, v144
	v_ashrrev_i32_e32 v141, 31, v140
	v_lshl_add_u64 v[142:143], v[140:141], 3, s[10:11]
	global_load_dwordx2 v[226:227], v[142:143], off offset:1024
	global_load_dwordx2 v[142:143], v[142:143], off
	v_add_u32_e32 v140, 0x80, v140
	s_waitcnt vmcnt(0)
	v_ffbh_u32_e32 v141, v143
	v_min_u32_e32 v141, 32, v141
	v_lshlrev_b64 v[142:143], v141, v[142:143]
	v_min_u32_e32 v142, 1, v142
	v_or_b32_e32 v142, v143, v142
	v_cvt_f32_u32_e32 v142, v142
	v_sub_u32_e32 v141, 32, v141
	v_ldexp_f32 v141, v142, v141
	v_mul_f32_e32 v141, 0x33800000, v141
	v_fmamk_f32 v141, v141, 0x3a000000, v224
	v_cmp_gt_f32_e32 vcc, s89, v141
	v_mul_f32_e32 v142, 0x4f800000, v141
	s_nop 0
	v_cndmask_b32_e32 v141, v141, v142, vcc
	v_sqrt_f32_e32 v142, v141
	s_nop 0
	v_add_u32_e32 v143, -1, v142
	v_fma_f32 v145, -v143, v142, v141
	v_cmp_ge_f32_e64 s[38:39], 0, v145
	v_add_u32_e32 v145, 1, v142
	s_nop 0
	v_cndmask_b32_e64 v143, v142, v143, s[38:39]
	v_fma_f32 v142, -v145, v142, v141
	v_cmp_lt_f32_e64 s[38:39], 0, v142
	s_nop 1
	v_cndmask_b32_e64 v142, v143, v145, s[38:39]
	v_mul_f32_e32 v143, 0x37800000, v142
	v_cndmask_b32_e32 v142, v142, v143, vcc
	v_cmp_class_f32_e32 vcc, v141, v225
	s_nop 1
	v_cndmask_b32_e32 v141, v142, v141, vcc
	v_div_scale_f32 v142, s[28:29], v141, v141, 1.0
	v_rcp_f32_e32 v143, v142
	s_nop 0
	v_fma_f32 v145, -v142, v143, 1.0
	v_fmac_f32_e32 v143, v145, v143
	v_div_scale_f32 v145, vcc, 1.0, v141, 1.0
	v_mul_f32_e32 v146, v145, v143
	v_fma_f32 v147, -v142, v146, v145
	v_fmac_f32_e32 v146, v147, v143
	v_fma_f32 v142, -v142, v146, v145
	v_div_fmas_f32 v142, v142, v143, v146
	v_div_fixup_f32 v142, v142, v141, 1.0
	v_mov_b32_e32 v140, v226
	v_mov_b32_e32 v141, v227
	v_lshl_add_u32 v143, v144, 2, s1
	s_waitcnt vmcnt(0)
	v_ffbh_u32_e32 v144, v141
	v_min_u32_e32 v144, 32, v144
	v_lshlrev_b64 v[140:141], v144, v[140:141]
	v_min_u32_e32 v140, 1, v140
	v_or_b32_e32 v140, v141, v140
	v_cvt_f32_u32_e32 v140, v140
	v_sub_u32_e32 v141, 32, v144
	v_ldexp_f32 v140, v140, v141
	v_mul_f32_e32 v140, 0x33800000, v140
	v_fmamk_f32 v140, v140, 0x3a000000, v224
	v_cmp_gt_f32_e32 vcc, s89, v140
	v_mul_f32_e32 v141, 0x4f800000, v140
	s_nop 0
	v_cndmask_b32_e32 v140, v140, v141, vcc
	v_sqrt_f32_e32 v141, v140
	s_nop 0
	v_add_u32_e32 v144, -1, v141
	v_fma_f32 v145, -v144, v141, v140
	v_cmp_ge_f32_e64 s[38:39], 0, v145
	v_add_u32_e32 v145, 1, v141
	s_nop 0
	v_cndmask_b32_e64 v144, v141, v144, s[38:39]
	v_fma_f32 v141, -v145, v141, v140
	v_cmp_lt_f32_e64 s[38:39], 0, v141
	s_nop 1
	v_cndmask_b32_e64 v141, v144, v145, s[38:39]
	v_mul_f32_e32 v144, 0x37800000, v141
	v_cndmask_b32_e32 v141, v141, v144, vcc
	v_cmp_class_f32_e32 vcc, v140, v225
	s_nop 1
	v_cndmask_b32_e32 v140, v141, v140, vcc
	v_div_scale_f32 v141, s[28:29], v140, v140, 1.0
	v_rcp_f32_e32 v144, v141
	s_nop 0
	v_fma_f32 v145, -v141, v144, 1.0
	v_fmac_f32_e32 v144, v145, v144
	v_div_scale_f32 v145, vcc, 1.0, v140, 1.0
	v_mul_f32_e32 v146, v145, v144
	v_fma_f32 v147, -v141, v146, v145
	v_fmac_f32_e32 v146, v147, v144
	v_fma_f32 v141, -v141, v146, v145
	v_div_fmas_f32 v141, v141, v144, v146
	v_div_fixup_f32 v140, v141, v140, 1.0
	ds_write2st64_b32 v143, v142, v140 offset1:1
	s_waitcnt lgkmcnt(0)

.LBB0_433:
	s_cmp_lg_u32 s14, s2
	s_mov_b64 s[28:29], -1
	v_readlane_b32 s68, v253, 22
	v_readlane_b32 s69, v253, 23
	s_cbranch_scc0 .LBB0_435
	s_lshl_b32 s5, s14, 8
	s_add_i32 s21, s5, s46
	v_mbcnt_lo_u32_b32 v136, -1, 0
	v_mbcnt_hi_u32_b32 v136, -1, v136
	s_nop 0
	v_add_u32_e32 v132, s21, v136
	v_ashrrev_i32_e32 v133, 31, v132
	v_lshl_add_u64 v[134:135], v[132:133], 3, s[18:19]
	global_load_dwordx2 v[226:227], v[134:135], off offset:1024
	global_load_dwordx2 v[134:135], v[134:135], off
	v_add_u32_e32 v132, 0x80, v132
	s_waitcnt vmcnt(0)
	v_ffbh_u32_e32 v133, v135
	v_min_u32_e32 v133, 32, v133
	v_lshlrev_b64 v[134:135], v133, v[134:135]
	v_min_u32_e32 v134, 1, v134
	v_or_b32_e32 v134, v135, v134
	v_cvt_f32_u32_e32 v134, v134
	v_sub_u32_e32 v133, 32, v133
	v_ldexp_f32 v133, v134, v133
	v_mul_f32_e32 v133, 0x33800000, v133
	v_fmamk_f32 v133, v133, 0x3a000000, v224
	v_cmp_gt_f32_e32 vcc, s89, v133
	v_mul_f32_e32 v134, 0x4f800000, v133
	s_nop 0
	v_cndmask_b32_e32 v133, v133, v134, vcc
	v_sqrt_f32_e32 v134, v133
	s_nop 0
	v_add_u32_e32 v135, -1, v134
	v_fma_f32 v137, -v135, v134, v133
	v_cmp_ge_f32_e64 s[42:43], 0, v137
	v_add_u32_e32 v137, 1, v134
	s_nop 0
	v_cndmask_b32_e64 v135, v134, v135, s[42:43]
	v_fma_f32 v134, -v137, v134, v133
	v_cmp_lt_f32_e64 s[42:43], 0, v134
	s_nop 1
	v_cndmask_b32_e64 v134, v135, v137, s[42:43]
	v_mul_f32_e32 v135, 0x37800000, v134
	v_cndmask_b32_e32 v134, v134, v135, vcc
	v_cmp_class_f32_e32 vcc, v133, v225
	s_nop 1
	v_cndmask_b32_e32 v133, v134, v133, vcc
	v_div_scale_f32 v134, s[28:29], v133, v133, 1.0
	v_rcp_f32_e32 v135, v134
	s_nop 0
	v_fma_f32 v137, -v134, v135, 1.0
	v_fmac_f32_e32 v135, v137, v135
	v_div_scale_f32 v137, vcc, 1.0, v133, 1.0
	v_mul_f32_e32 v138, v137, v135
	v_fma_f32 v139, -v134, v138, v137
	v_fmac_f32_e32 v138, v139, v135
	v_fma_f32 v134, -v134, v138, v137
	v_div_fmas_f32 v134, v134, v135, v138
	v_div_fixup_f32 v134, v134, v133, 1.0
	v_mov_b32_e32 v132, v226
	v_mov_b32_e32 v133, v227
	v_lshl_add_u32 v135, v136, 2, s56
	s_waitcnt vmcnt(0)
	v_ffbh_u32_e32 v136, v133
	v_min_u32_e32 v136, 32, v136
	v_lshlrev_b64 v[132:133], v136, v[132:133]
	v_min_u32_e32 v132, 1, v132
	v_or_b32_e32 v132, v133, v132
	v_cvt_f32_u32_e32 v132, v132
	v_sub_u32_e32 v133, 32, v136
	v_ldexp_f32 v132, v132, v133
	v_mul_f32_e32 v132, 0x33800000, v132
	v_fmamk_f32 v132, v132, 0x3a000000, v224
	v_cmp_gt_f32_e32 vcc, s89, v132
	v_mul_f32_e32 v133, 0x4f800000, v132
	s_nop 0
	v_cndmask_b32_e32 v132, v132, v133, vcc
	v_sqrt_f32_e32 v133, v132
	s_nop 0
	v_add_u32_e32 v136, -1, v133
	v_fma_f32 v137, -v136, v133, v132
	v_cmp_ge_f32_e64 s[42:43], 0, v137
	v_add_u32_e32 v137, 1, v133
	s_nop 0
	v_cndmask_b32_e64 v136, v133, v136, s[42:43]
	v_fma_f32 v133, -v137, v133, v132
	v_cmp_lt_f32_e64 s[42:43], 0, v133
	s_nop 1
	v_cndmask_b32_e64 v133, v136, v137, s[42:43]
	v_mul_f32_e32 v136, 0x37800000, v133
	v_cndmask_b32_e32 v133, v133, v136, vcc
	v_cmp_class_f32_e32 vcc, v132, v225
	s_nop 1
	v_cndmask_b32_e32 v132, v133, v132, vcc
	v_div_scale_f32 v133, s[28:29], v132, v132, 1.0
	v_rcp_f32_e32 v136, v133
	s_mov_b64 s[28:29], 0
	v_fma_f32 v137, -v133, v136, 1.0
	v_fmac_f32_e32 v136, v137, v136
	v_div_scale_f32 v137, vcc, 1.0, v132, 1.0
	v_mul_f32_e32 v138, v137, v136
	v_fma_f32 v139, -v133, v138, v137
	v_fmac_f32_e32 v138, v139, v136
	v_fma_f32 v133, -v133, v138, v137
	v_div_fmas_f32 v133, v133, v136, v138
	v_div_fixup_f32 v132, v133, v132, 1.0
	ds_write2st64_b32 v135, v134, v132 offset1:1
	s_waitcnt lgkmcnt(0)
